# P1 rows in two passes: rstd + XB (bf16 x) stores first, which need no modulation vectors, then the XN pass - the modulation-vector load latency after the grid barrier is hidden
# speedup vs baseline: 1.0092x; 1.0017x over previous
.Lp1_pfd:
	s_waitcnt vmcnt(8)
.Lp1_rows:
	v_mov_b64_e32 v[80:81], v[64:65]
	s_cmp_eq_u32 s97, 1
	s_cbranch_scc1 .Lp1_nw0
	s_waitcnt vmcnt(28)
.Lp1_nw0:
	v_pk_mul_f32 v[90:91], v[116:117], v[116:117]
	v_pk_mul_f32 v[92:93], v[114:115], v[114:115]
	v_pk_mul_f32 v[100:101], v[120:121], v[120:121]
	v_pk_mul_f32 v[102:103], v[118:119], v[118:119]
	v_pk_mov_b32 v[108:109], v[92:93], v[90:91] op_sel:[1,0]
	v_mov_b32_e32 v93, v91
	v_pk_mov_b32 v[90:91], v[102:103], v[100:101] op_sel:[1,0]
	v_mov_b32_e32 v103, v101
	v_mul_f32_e32 v107, v129, v129
	v_mul_f32_e32 v104, v123, v123
	v_mul_f32_e32 v106, v125, v125
	v_pk_add_f32 v[92:93], v[108:109], v[92:93]
	v_pk_add_f32 v[90:91], v[90:91], v[102:103]
	v_mul_f32_e32 v89, v128, v128
	v_mul_f32_e32 v110, v126, v126
	v_mul_f32_e32 v111, v127, v127
	v_pk_fma_f32 v[100:101], v[122:123], v[122:123], v[104:105] op_sel_hi:[1,1,0]
	v_pk_fma_f32 v[104:105], v[124:125], v[124:125], v[106:107] op_sel_hi:[1,1,0]
	v_pk_add_f32 v[92:93], v[92:93], v[92:93] op_sel:[0,1] op_sel_hi:[1,0]
	v_pk_add_f32 v[90:91], v[90:91], v[90:91] op_sel:[0,1] op_sel_hi:[1,0]
	v_mov_b32_e32 v101, v89
	v_mov_b32_e32 v105, v107
	v_mov_b32_e32 v93, v110
	v_mov_b32_e32 v91, v111
	v_pk_add_f32 v[100:101], v[100:101], v[104:105]
	v_pk_add_f32 v[90:91], v[92:93], v[90:91]
	s_nop 0
	v_pk_add_f32 v[90:91], v[90:91], v[100:101]
	s_nop 0
	v_add_f32_e32 v89, v90, v91
	s_nop 1
	v_add_f32_dpp v89, v89, v89 quad_perm:[1,0,3,2] row_mask:0xf bank_mask:0xf bound_ctrl:1
	s_nop 1
	v_add_f32_dpp v89, v89, v89 quad_perm:[2,3,0,1] row_mask:0xf bank_mask:0xf bound_ctrl:1
	s_nop 1
	v_add_f32_dpp v89, v89, v89 row_half_mirror row_mask:0xf bank_mask:0xf bound_ctrl:1
	s_nop 1
	v_add_f32_dpp v89, v89, v89 row_mirror row_mask:0xf bank_mask:0xf bound_ctrl:1
	s_nop 0
	v_readlane_b32 s0, v89, 16
	v_readlane_b32 s28, v89, 48
	v_readlane_b32 s26, v89, 0
	v_readlane_b32 s27, v89, 32
	v_mov_b32_e32 v90, s0
	v_mov_b32_e32 v91, s28
	v_pk_add_f32 v[90:91], s[26:27], v[90:91]
	s_nop 0
	v_add_f32_e32 v89, v90, v91
	v_fmamk_f32 v89, v89, 0x3a800000, v88
	v_rsq_f32_e32 v72, v89
	v_cvt_pk_bf16_f32 v34, v114, v115
	v_cvt_pk_bf16_f32 v35, v116, v117
	v_cvt_pk_bf16_f32 v36, v118, v119
	v_cvt_pk_bf16_f32 v37, v120, v121
	v_lshl_add_u64 v[70:71], v[64:65], 0, s[46:47]
	global_store_dwordx4 v[64:65], v[34:37], off sc1
	s_nop 1
	v_cvt_pk_bf16_f32 v34, v122, v123
	v_cvt_pk_bf16_f32 v35, v124, v125
	v_cvt_pk_bf16_f32 v36, v126, v127
	v_cvt_pk_bf16_f32 v37, v128, v129
	s_nop 0
	global_store_dwordx4 v[70:71], v[34:37], off sc1
	s_nop 1
	v_lshl_add_u64 v[64:65], v[64:65], 0, s[76:77]
	s_cmp_eq_u32 s97, 1
	s_cbranch_scc1 .Lp1_nw1
	s_waitcnt vmcnt(26)
.Lp1_nw1:
	v_pk_mul_f32 v[90:91], v[132:133], v[132:133]
	v_pk_mul_f32 v[92:93], v[130:131], v[130:131]
	v_pk_mul_f32 v[100:101], v[136:137], v[136:137]
	v_pk_mul_f32 v[102:103], v[134:135], v[134:135]
	v_pk_mov_b32 v[108:109], v[92:93], v[90:91] op_sel:[1,0]
	v_mov_b32_e32 v93, v91
	v_pk_mov_b32 v[90:91], v[102:103], v[100:101] op_sel:[1,0]
	v_mov_b32_e32 v103, v101
	v_mul_f32_e32 v107, v145, v145
	v_mul_f32_e32 v104, v139, v139
	v_mul_f32_e32 v106, v141, v141
	v_pk_add_f32 v[92:93], v[108:109], v[92:93]
	v_pk_add_f32 v[90:91], v[90:91], v[102:103]
	v_mul_f32_e32 v89, v144, v144
	v_mul_f32_e32 v110, v142, v142
	v_mul_f32_e32 v111, v143, v143
	v_pk_fma_f32 v[100:101], v[138:139], v[138:139], v[104:105] op_sel_hi:[1,1,0]
	v_pk_fma_f32 v[104:105], v[140:141], v[140:141], v[106:107] op_sel_hi:[1,1,0]
	v_pk_add_f32 v[92:93], v[92:93], v[92:93] op_sel:[0,1] op_sel_hi:[1,0]
	v_pk_add_f32 v[90:91], v[90:91], v[90:91] op_sel:[0,1] op_sel_hi:[1,0]
	v_mov_b32_e32 v101, v89
	v_mov_b32_e32 v105, v107
	v_mov_b32_e32 v93, v110
	v_mov_b32_e32 v91, v111
	v_pk_add_f32 v[100:101], v[100:101], v[104:105]
	v_pk_add_f32 v[90:91], v[92:93], v[90:91]
	s_nop 0
	v_pk_add_f32 v[90:91], v[90:91], v[100:101]
	s_nop 0
	v_add_f32_e32 v89, v90, v91
	s_nop 1
	v_add_f32_dpp v89, v89, v89 quad_perm:[1,0,3,2] row_mask:0xf bank_mask:0xf bound_ctrl:1
	s_nop 1
	v_add_f32_dpp v89, v89, v89 quad_perm:[2,3,0,1] row_mask:0xf bank_mask:0xf bound_ctrl:1
	s_nop 1
	v_add_f32_dpp v89, v89, v89 row_half_mirror row_mask:0xf bank_mask:0xf bound_ctrl:1
	s_nop 1
	v_add_f32_dpp v89, v89, v89 row_mirror row_mask:0xf bank_mask:0xf bound_ctrl:1
	s_nop 0
	v_readlane_b32 s0, v89, 16
	v_readlane_b32 s28, v89, 48
	v_readlane_b32 s26, v89, 0
	v_readlane_b32 s27, v89, 32
	v_mov_b32_e32 v90, s0
	v_mov_b32_e32 v91, s28
	v_pk_add_f32 v[90:91], s[26:27], v[90:91]
	s_nop 0
	v_add_f32_e32 v89, v90, v91
	v_fmamk_f32 v89, v89, 0x3a800000, v88
	v_rsq_f32_e32 v73, v89
	v_cvt_pk_bf16_f32 v34, v130, v131
	v_cvt_pk_bf16_f32 v35, v132, v133
	v_cvt_pk_bf16_f32 v36, v134, v135
	v_cvt_pk_bf16_f32 v37, v136, v137
	v_lshl_add_u64 v[70:71], v[64:65], 0, s[46:47]
	global_store_dwordx4 v[64:65], v[34:37], off sc1
	s_nop 1
	v_cvt_pk_bf16_f32 v34, v138, v139
	v_cvt_pk_bf16_f32 v35, v140, v141
	v_cvt_pk_bf16_f32 v36, v142, v143
	v_cvt_pk_bf16_f32 v37, v144, v145
	s_nop 0
	global_store_dwordx4 v[70:71], v[34:37], off sc1
	s_nop 1
	v_lshl_add_u64 v[64:65], v[64:65], 0, s[76:77]
	s_cmp_eq_u32 s97, 1
	s_cbranch_scc1 .Lp1_nw2
	s_waitcnt vmcnt(24)
.Lp1_nw2:
	v_pk_mul_f32 v[90:91], v[148:149], v[148:149]
	v_pk_mul_f32 v[92:93], v[146:147], v[146:147]
	v_pk_mul_f32 v[100:101], v[152:153], v[152:153]
	v_pk_mul_f32 v[102:103], v[150:151], v[150:151]
	v_pk_mov_b32 v[108:109], v[92:93], v[90:91] op_sel:[1,0]
	v_mov_b32_e32 v93, v91
	v_pk_mov_b32 v[90:91], v[102:103], v[100:101] op_sel:[1,0]
	v_mov_b32_e32 v103, v101
	v_mul_f32_e32 v107, v161, v161
	v_mul_f32_e32 v104, v155, v155
	v_mul_f32_e32 v106, v157, v157
	v_pk_add_f32 v[92:93], v[108:109], v[92:93]
	v_pk_add_f32 v[90:91], v[90:91], v[102:103]
	v_mul_f32_e32 v89, v160, v160
	v_mul_f32_e32 v110, v158, v158
	v_mul_f32_e32 v111, v159, v159
	v_pk_fma_f32 v[100:101], v[154:155], v[154:155], v[104:105] op_sel_hi:[1,1,0]
	v_pk_fma_f32 v[104:105], v[156:157], v[156:157], v[106:107] op_sel_hi:[1,1,0]
	v_pk_add_f32 v[92:93], v[92:93], v[92:93] op_sel:[0,1] op_sel_hi:[1,0]
	v_pk_add_f32 v[90:91], v[90:91], v[90:91] op_sel:[0,1] op_sel_hi:[1,0]
	v_mov_b32_e32 v101, v89
	v_mov_b32_e32 v105, v107
	v_mov_b32_e32 v93, v110
	v_mov_b32_e32 v91, v111
	v_pk_add_f32 v[100:101], v[100:101], v[104:105]
	v_pk_add_f32 v[90:91], v[92:93], v[90:91]
	s_nop 0
	v_pk_add_f32 v[90:91], v[90:91], v[100:101]
	s_nop 0
	v_add_f32_e32 v89, v90, v91
	s_nop 1
	v_add_f32_dpp v89, v89, v89 quad_perm:[1,0,3,2] row_mask:0xf bank_mask:0xf bound_ctrl:1
	s_nop 1
	v_add_f32_dpp v89, v89, v89 quad_perm:[2,3,0,1] row_mask:0xf bank_mask:0xf bound_ctrl:1
	s_nop 1
	v_add_f32_dpp v89, v89, v89 row_half_mirror row_mask:0xf bank_mask:0xf bound_ctrl:1
	s_nop 1
	v_add_f32_dpp v89, v89, v89 row_mirror row_mask:0xf bank_mask:0xf bound_ctrl:1
	s_nop 0
	v_readlane_b32 s0, v89, 16
	v_readlane_b32 s28, v89, 48
	v_readlane_b32 s26, v89, 0
	v_readlane_b32 s27, v89, 32
	v_mov_b32_e32 v90, s0
	v_mov_b32_e32 v91, s28
	v_pk_add_f32 v[90:91], s[26:27], v[90:91]
	s_nop 0
	v_add_f32_e32 v89, v90, v91
	v_fmamk_f32 v89, v89, 0x3a800000, v88
	v_rsq_f32_e32 v74, v89
	v_cvt_pk_bf16_f32 v34, v146, v147
	v_cvt_pk_bf16_f32 v35, v148, v149
	v_cvt_pk_bf16_f32 v36, v150, v151
	v_cvt_pk_bf16_f32 v37, v152, v153
	v_lshl_add_u64 v[70:71], v[64:65], 0, s[46:47]
	global_store_dwordx4 v[64:65], v[34:37], off sc1
	s_nop 1
	v_cvt_pk_bf16_f32 v34, v154, v155
	v_cvt_pk_bf16_f32 v35, v156, v157
	v_cvt_pk_bf16_f32 v36, v158, v159
	v_cvt_pk_bf16_f32 v37, v160, v161
	s_nop 0
	global_store_dwordx4 v[70:71], v[34:37], off sc1
	s_nop 1
	v_lshl_add_u64 v[64:65], v[64:65], 0, s[76:77]
	s_cmp_eq_u32 s97, 1
	s_cbranch_scc1 .Lp1_nw3
	s_waitcnt vmcnt(22)
.Lp1_nw3:
	v_pk_mul_f32 v[90:91], v[164:165], v[164:165]
	v_pk_mul_f32 v[92:93], v[162:163], v[162:163]
	v_pk_mul_f32 v[100:101], v[168:169], v[168:169]
	v_pk_mul_f32 v[102:103], v[166:167], v[166:167]
	v_pk_mov_b32 v[108:109], v[92:93], v[90:91] op_sel:[1,0]
	v_mov_b32_e32 v93, v91
	v_pk_mov_b32 v[90:91], v[102:103], v[100:101] op_sel:[1,0]
	v_mov_b32_e32 v103, v101
	v_mul_f32_e32 v107, v177, v177
	v_mul_f32_e32 v104, v171, v171
	v_mul_f32_e32 v106, v173, v173
	v_pk_add_f32 v[92:93], v[108:109], v[92:93]
	v_pk_add_f32 v[90:91], v[90:91], v[102:103]
	v_mul_f32_e32 v89, v176, v176
	v_mul_f32_e32 v110, v174, v174
	v_mul_f32_e32 v111, v175, v175
	v_pk_fma_f32 v[100:101], v[170:171], v[170:171], v[104:105] op_sel_hi:[1,1,0]
	v_pk_fma_f32 v[104:105], v[172:173], v[172:173], v[106:107] op_sel_hi:[1,1,0]
	v_pk_add_f32 v[92:93], v[92:93], v[92:93] op_sel:[0,1] op_sel_hi:[1,0]
	v_pk_add_f32 v[90:91], v[90:91], v[90:91] op_sel:[0,1] op_sel_hi:[1,0]
	v_mov_b32_e32 v101, v89
	v_mov_b32_e32 v105, v107
	v_mov_b32_e32 v93, v110
	v_mov_b32_e32 v91, v111
	v_pk_add_f32 v[100:101], v[100:101], v[104:105]
	v_pk_add_f32 v[90:91], v[92:93], v[90:91]
	s_nop 0
	v_pk_add_f32 v[90:91], v[90:91], v[100:101]
	s_nop 0
	v_add_f32_e32 v89, v90, v91
	s_nop 1
	v_add_f32_dpp v89, v89, v89 quad_perm:[1,0,3,2] row_mask:0xf bank_mask:0xf bound_ctrl:1
	s_nop 1
	v_add_f32_dpp v89, v89, v89 quad_perm:[2,3,0,1] row_mask:0xf bank_mask:0xf bound_ctrl:1
	s_nop 1
	v_add_f32_dpp v89, v89, v89 row_half_mirror row_mask:0xf bank_mask:0xf bound_ctrl:1
	s_nop 1
	v_add_f32_dpp v89, v89, v89 row_mirror row_mask:0xf bank_mask:0xf bound_ctrl:1
	s_nop 0
	v_readlane_b32 s0, v89, 16
	v_readlane_b32 s28, v89, 48
	v_readlane_b32 s26, v89, 0
	v_readlane_b32 s27, v89, 32
	v_mov_b32_e32 v90, s0
	v_mov_b32_e32 v91, s28
	v_pk_add_f32 v[90:91], s[26:27], v[90:91]
	s_nop 0
	v_add_f32_e32 v89, v90, v91
	v_fmamk_f32 v89, v89, 0x3a800000, v88
	v_rsq_f32_e32 v75, v89
	v_cvt_pk_bf16_f32 v34, v162, v163
	v_cvt_pk_bf16_f32 v35, v164, v165
	v_cvt_pk_bf16_f32 v36, v166, v167
	v_cvt_pk_bf16_f32 v37, v168, v169
	v_lshl_add_u64 v[70:71], v[64:65], 0, s[46:47]
	global_store_dwordx4 v[64:65], v[34:37], off sc1
	s_nop 1
	v_cvt_pk_bf16_f32 v34, v170, v171
	v_cvt_pk_bf16_f32 v35, v172, v173
	v_cvt_pk_bf16_f32 v36, v174, v175
	v_cvt_pk_bf16_f32 v37, v176, v177
	s_nop 0
	global_store_dwordx4 v[70:71], v[34:37], off sc1
	s_nop 1
	v_lshl_add_u64 v[64:65], v[64:65], 0, s[76:77]
	s_cmp_eq_u32 s97, 1
	s_cbranch_scc1 .Lp1_nw4
	s_waitcnt vmcnt(20)
.Lp1_nw4:
	v_pk_mul_f32 v[90:91], v[180:181], v[180:181]
	v_pk_mul_f32 v[92:93], v[178:179], v[178:179]
	v_pk_mul_f32 v[100:101], v[184:185], v[184:185]
	v_pk_mul_f32 v[102:103], v[182:183], v[182:183]
	v_pk_mov_b32 v[108:109], v[92:93], v[90:91] op_sel:[1,0]
	v_mov_b32_e32 v93, v91
	v_pk_mov_b32 v[90:91], v[102:103], v[100:101] op_sel:[1,0]
	v_mov_b32_e32 v103, v101
	v_mul_f32_e32 v107, v193, v193
	v_mul_f32_e32 v104, v187, v187
	v_mul_f32_e32 v106, v189, v189
	v_pk_add_f32 v[92:93], v[108:109], v[92:93]
	v_pk_add_f32 v[90:91], v[90:91], v[102:103]
	v_mul_f32_e32 v89, v192, v192
	v_mul_f32_e32 v110, v190, v190
	v_mul_f32_e32 v111, v191, v191
	v_pk_fma_f32 v[100:101], v[186:187], v[186:187], v[104:105] op_sel_hi:[1,1,0]
	v_pk_fma_f32 v[104:105], v[188:189], v[188:189], v[106:107] op_sel_hi:[1,1,0]
	v_pk_add_f32 v[92:93], v[92:93], v[92:93] op_sel:[0,1] op_sel_hi:[1,0]
	v_pk_add_f32 v[90:91], v[90:91], v[90:91] op_sel:[0,1] op_sel_hi:[1,0]
	v_mov_b32_e32 v101, v89
	v_mov_b32_e32 v105, v107
	v_mov_b32_e32 v93, v110
	v_mov_b32_e32 v91, v111
	v_pk_add_f32 v[100:101], v[100:101], v[104:105]
	v_pk_add_f32 v[90:91], v[92:93], v[90:91]
	s_nop 0
	v_pk_add_f32 v[90:91], v[90:91], v[100:101]
	s_nop 0
	v_add_f32_e32 v89, v90, v91
	s_nop 1
	v_add_f32_dpp v89, v89, v89 quad_perm:[1,0,3,2] row_mask:0xf bank_mask:0xf bound_ctrl:1
	s_nop 1
	v_add_f32_dpp v89, v89, v89 quad_perm:[2,3,0,1] row_mask:0xf bank_mask:0xf bound_ctrl:1
	s_nop 1
	v_add_f32_dpp v89, v89, v89 row_half_mirror row_mask:0xf bank_mask:0xf bound_ctrl:1
	s_nop 1
	v_add_f32_dpp v89, v89, v89 row_mirror row_mask:0xf bank_mask:0xf bound_ctrl:1
	s_nop 0
	v_readlane_b32 s0, v89, 16
	v_readlane_b32 s28, v89, 48
	v_readlane_b32 s26, v89, 0
	v_readlane_b32 s27, v89, 32
	v_mov_b32_e32 v90, s0
	v_mov_b32_e32 v91, s28
	v_pk_add_f32 v[90:91], s[26:27], v[90:91]
	s_nop 0
	v_add_f32_e32 v89, v90, v91
	v_fmamk_f32 v89, v89, 0x3a800000, v88
	v_rsq_f32_e32 v76, v89
	v_cvt_pk_bf16_f32 v34, v178, v179
	v_cvt_pk_bf16_f32 v35, v180, v181
	v_cvt_pk_bf16_f32 v36, v182, v183
	v_cvt_pk_bf16_f32 v37, v184, v185
	v_lshl_add_u64 v[70:71], v[64:65], 0, s[46:47]
	global_store_dwordx4 v[64:65], v[34:37], off sc1
	s_nop 1
	v_cvt_pk_bf16_f32 v34, v186, v187
	v_cvt_pk_bf16_f32 v35, v188, v189
	v_cvt_pk_bf16_f32 v36, v190, v191
	v_cvt_pk_bf16_f32 v37, v192, v193
	s_nop 0
	global_store_dwordx4 v[70:71], v[34:37], off sc1
	s_nop 1
	v_lshl_add_u64 v[64:65], v[64:65], 0, s[76:77]
	s_cmp_eq_u32 s97, 1
	s_cbranch_scc1 .Lp1_nw5
	s_waitcnt vmcnt(18)
.Lp1_nw5:
	v_pk_mul_f32 v[90:91], v[196:197], v[196:197]
	v_pk_mul_f32 v[92:93], v[194:195], v[194:195]
	v_pk_mul_f32 v[100:101], v[200:201], v[200:201]
	v_pk_mul_f32 v[102:103], v[198:199], v[198:199]
	v_pk_mov_b32 v[108:109], v[92:93], v[90:91] op_sel:[1,0]
	v_mov_b32_e32 v93, v91
	v_pk_mov_b32 v[90:91], v[102:103], v[100:101] op_sel:[1,0]
	v_mov_b32_e32 v103, v101
	v_mul_f32_e32 v107, v209, v209
	v_mul_f32_e32 v104, v203, v203
	v_mul_f32_e32 v106, v205, v205
	v_pk_add_f32 v[92:93], v[108:109], v[92:93]
	v_pk_add_f32 v[90:91], v[90:91], v[102:103]
	v_mul_f32_e32 v89, v208, v208
	v_mul_f32_e32 v110, v206, v206
	v_mul_f32_e32 v111, v207, v207
	v_pk_fma_f32 v[100:101], v[202:203], v[202:203], v[104:105] op_sel_hi:[1,1,0]
	v_pk_fma_f32 v[104:105], v[204:205], v[204:205], v[106:107] op_sel_hi:[1,1,0]
	v_pk_add_f32 v[92:93], v[92:93], v[92:93] op_sel:[0,1] op_sel_hi:[1,0]
	v_pk_add_f32 v[90:91], v[90:91], v[90:91] op_sel:[0,1] op_sel_hi:[1,0]
	v_mov_b32_e32 v101, v89
	v_mov_b32_e32 v105, v107
	v_mov_b32_e32 v93, v110
	v_mov_b32_e32 v91, v111
	v_pk_add_f32 v[100:101], v[100:101], v[104:105]
	v_pk_add_f32 v[90:91], v[92:93], v[90:91]
	s_nop 0
	v_pk_add_f32 v[90:91], v[90:91], v[100:101]
	s_nop 0
	v_add_f32_e32 v89, v90, v91
	s_nop 1
	v_add_f32_dpp v89, v89, v89 quad_perm:[1,0,3,2] row_mask:0xf bank_mask:0xf bound_ctrl:1
	s_nop 1
	v_add_f32_dpp v89, v89, v89 quad_perm:[2,3,0,1] row_mask:0xf bank_mask:0xf bound_ctrl:1
	s_nop 1
	v_add_f32_dpp v89, v89, v89 row_half_mirror row_mask:0xf bank_mask:0xf bound_ctrl:1
	s_nop 1
	v_add_f32_dpp v89, v89, v89 row_mirror row_mask:0xf bank_mask:0xf bound_ctrl:1
	s_nop 0
	v_readlane_b32 s0, v89, 16
	v_readlane_b32 s28, v89, 48
	v_readlane_b32 s26, v89, 0
	v_readlane_b32 s27, v89, 32
	v_mov_b32_e32 v90, s0
	v_mov_b32_e32 v91, s28
	v_pk_add_f32 v[90:91], s[26:27], v[90:91]
	s_nop 0
	v_add_f32_e32 v89, v90, v91
	v_fmamk_f32 v89, v89, 0x3a800000, v88
	v_rsq_f32_e32 v77, v89
	v_cvt_pk_bf16_f32 v34, v194, v195
	v_cvt_pk_bf16_f32 v35, v196, v197
	v_cvt_pk_bf16_f32 v36, v198, v199
	v_cvt_pk_bf16_f32 v37, v200, v201
	v_lshl_add_u64 v[70:71], v[64:65], 0, s[46:47]
	global_store_dwordx4 v[64:65], v[34:37], off sc1
	s_nop 1
	v_cvt_pk_bf16_f32 v34, v202, v203
	v_cvt_pk_bf16_f32 v35, v204, v205
	v_cvt_pk_bf16_f32 v36, v206, v207
	v_cvt_pk_bf16_f32 v37, v208, v209
	s_nop 0
	global_store_dwordx4 v[70:71], v[34:37], off sc1
	s_nop 1
	v_lshl_add_u64 v[64:65], v[64:65], 0, s[76:77]
	s_cmp_eq_u32 s97, 1
	s_cbranch_scc1 .Lp1_nw6
	s_waitcnt vmcnt(16)
.Lp1_nw6:
	v_pk_mul_f32 v[90:91], v[212:213], v[212:213]
	v_pk_mul_f32 v[92:93], v[210:211], v[210:211]
	v_pk_mul_f32 v[100:101], v[216:217], v[216:217]
	v_pk_mul_f32 v[102:103], v[214:215], v[214:215]
	v_pk_mov_b32 v[108:109], v[92:93], v[90:91] op_sel:[1,0]
	v_mov_b32_e32 v93, v91
	v_pk_mov_b32 v[90:91], v[102:103], v[100:101] op_sel:[1,0]
	v_mov_b32_e32 v103, v101
	v_mul_f32_e32 v107, v225, v225
	v_mul_f32_e32 v104, v219, v219
	v_mul_f32_e32 v106, v221, v221
	v_pk_add_f32 v[92:93], v[108:109], v[92:93]
	v_pk_add_f32 v[90:91], v[90:91], v[102:103]
	v_mul_f32_e32 v89, v224, v224
	v_mul_f32_e32 v110, v222, v222
	v_mul_f32_e32 v111, v223, v223
	v_pk_fma_f32 v[100:101], v[218:219], v[218:219], v[104:105] op_sel_hi:[1,1,0]
	v_pk_fma_f32 v[104:105], v[220:221], v[220:221], v[106:107] op_sel_hi:[1,1,0]
	v_pk_add_f32 v[92:93], v[92:93], v[92:93] op_sel:[0,1] op_sel_hi:[1,0]
	v_pk_add_f32 v[90:91], v[90:91], v[90:91] op_sel:[0,1] op_sel_hi:[1,0]
	v_mov_b32_e32 v101, v89
	v_mov_b32_e32 v105, v107
	v_mov_b32_e32 v93, v110
	v_mov_b32_e32 v91, v111
	v_pk_add_f32 v[100:101], v[100:101], v[104:105]
	v_pk_add_f32 v[90:91], v[92:93], v[90:91]
	s_nop 0
	v_pk_add_f32 v[90:91], v[90:91], v[100:101]
	s_nop 0
	v_add_f32_e32 v89, v90, v91
	s_nop 1
	v_add_f32_dpp v89, v89, v89 quad_perm:[1,0,3,2] row_mask:0xf bank_mask:0xf bound_ctrl:1
	s_nop 1
	v_add_f32_dpp v89, v89, v89 quad_perm:[2,3,0,1] row_mask:0xf bank_mask:0xf bound_ctrl:1
	s_nop 1
	v_add_f32_dpp v89, v89, v89 row_half_mirror row_mask:0xf bank_mask:0xf bound_ctrl:1
	s_nop 1
	v_add_f32_dpp v89, v89, v89 row_mirror row_mask:0xf bank_mask:0xf bound_ctrl:1
	s_nop 0
	v_readlane_b32 s0, v89, 16
	v_readlane_b32 s28, v89, 48
	v_readlane_b32 s26, v89, 0
	v_readlane_b32 s27, v89, 32
	v_mov_b32_e32 v90, s0
	v_mov_b32_e32 v91, s28
	v_pk_add_f32 v[90:91], s[26:27], v[90:91]
	s_nop 0
	v_add_f32_e32 v89, v90, v91
	v_fmamk_f32 v89, v89, 0x3a800000, v88
	v_rsq_f32_e32 v78, v89
	v_cvt_pk_bf16_f32 v34, v210, v211
	v_cvt_pk_bf16_f32 v35, v212, v213
	v_cvt_pk_bf16_f32 v36, v214, v215
	v_cvt_pk_bf16_f32 v37, v216, v217
	v_lshl_add_u64 v[70:71], v[64:65], 0, s[46:47]
	global_store_dwordx4 v[64:65], v[34:37], off sc1
	s_nop 1
	v_cvt_pk_bf16_f32 v34, v218, v219
	v_cvt_pk_bf16_f32 v35, v220, v221
	v_cvt_pk_bf16_f32 v36, v222, v223
	v_cvt_pk_bf16_f32 v37, v224, v225
	s_nop 0
	global_store_dwordx4 v[70:71], v[34:37], off sc1
	s_nop 1
	v_lshl_add_u64 v[64:65], v[64:65], 0, s[76:77]
	s_cmp_eq_u32 s97, 1
	s_cbranch_scc1 .Lp1_nw7
	s_waitcnt vmcnt(14)
.Lp1_nw7:
	v_pk_mul_f32 v[90:91], v[228:229], v[228:229]
	v_pk_mul_f32 v[92:93], v[226:227], v[226:227]
	v_pk_mul_f32 v[100:101], v[232:233], v[232:233]
	v_pk_mul_f32 v[102:103], v[230:231], v[230:231]
	v_pk_mov_b32 v[108:109], v[92:93], v[90:91] op_sel:[1,0]
	v_mov_b32_e32 v93, v91
	v_pk_mov_b32 v[90:91], v[102:103], v[100:101] op_sel:[1,0]
	v_mov_b32_e32 v103, v101
	v_mul_f32_e32 v107, v241, v241
	v_mul_f32_e32 v104, v235, v235
	v_mul_f32_e32 v106, v237, v237
	v_pk_add_f32 v[92:93], v[108:109], v[92:93]
	v_pk_add_f32 v[90:91], v[90:91], v[102:103]
	v_mul_f32_e32 v89, v240, v240
	v_mul_f32_e32 v110, v238, v238
	v_mul_f32_e32 v111, v239, v239
	v_pk_fma_f32 v[100:101], v[234:235], v[234:235], v[104:105] op_sel_hi:[1,1,0]
	v_pk_fma_f32 v[104:105], v[236:237], v[236:237], v[106:107] op_sel_hi:[1,1,0]
	v_pk_add_f32 v[92:93], v[92:93], v[92:93] op_sel:[0,1] op_sel_hi:[1,0]
	v_pk_add_f32 v[90:91], v[90:91], v[90:91] op_sel:[0,1] op_sel_hi:[1,0]
	v_mov_b32_e32 v101, v89
	v_mov_b32_e32 v105, v107
	v_mov_b32_e32 v93, v110
	v_mov_b32_e32 v91, v111
	v_pk_add_f32 v[100:101], v[100:101], v[104:105]
	v_pk_add_f32 v[90:91], v[92:93], v[90:91]
	s_nop 0
	v_pk_add_f32 v[90:91], v[90:91], v[100:101]
	s_nop 0
	v_add_f32_e32 v89, v90, v91
	s_nop 1
	v_add_f32_dpp v89, v89, v89 quad_perm:[1,0,3,2] row_mask:0xf bank_mask:0xf bound_ctrl:1
	s_nop 1
	v_add_f32_dpp v89, v89, v89 quad_perm:[2,3,0,1] row_mask:0xf bank_mask:0xf bound_ctrl:1
	s_nop 1
	v_add_f32_dpp v89, v89, v89 row_half_mirror row_mask:0xf bank_mask:0xf bound_ctrl:1
	s_nop 1
	v_add_f32_dpp v89, v89, v89 row_mirror row_mask:0xf bank_mask:0xf bound_ctrl:1
	s_nop 0
	v_readlane_b32 s0, v89, 16
	v_readlane_b32 s28, v89, 48
	v_readlane_b32 s26, v89, 0
	v_readlane_b32 s27, v89, 32
	v_mov_b32_e32 v90, s0
	v_mov_b32_e32 v91, s28
	v_pk_add_f32 v[90:91], s[26:27], v[90:91]
	s_nop 0
	v_add_f32_e32 v89, v90, v91
	v_fmamk_f32 v89, v89, 0x3a800000, v88
	v_rsq_f32_e32 v79, v89
	v_cvt_pk_bf16_f32 v34, v226, v227
	v_cvt_pk_bf16_f32 v35, v228, v229
	v_cvt_pk_bf16_f32 v36, v230, v231
	v_cvt_pk_bf16_f32 v37, v232, v233
	v_lshl_add_u64 v[70:71], v[64:65], 0, s[46:47]
	global_store_dwordx4 v[64:65], v[34:37], off sc1
	s_nop 1
	v_cvt_pk_bf16_f32 v34, v234, v235
	v_cvt_pk_bf16_f32 v35, v236, v237
	v_cvt_pk_bf16_f32 v36, v238, v239
	v_cvt_pk_bf16_f32 v37, v240, v241
	s_nop 0
	global_store_dwordx4 v[70:71], v[34:37], off sc1
	s_nop 1
	s_waitcnt vmcnt(16)
	v_mov_b64_e32 v[64:65], v[80:81]
	v_mov_b32_e32 v90, v72
	v_lshl_add_u64 v[66:67], v[64:65], 0, s[42:43]
	v_pk_mul_f32 v[92:93], v[114:115], v[90:91] op_sel_hi:[1,0]
	v_pk_mul_f32 v[100:101], v[116:117], v[90:91] op_sel_hi:[1,0]
	v_pk_mul_f32 v[102:103], v[118:119], v[90:91] op_sel_hi:[1,0]
	v_pk_mul_f32 v[104:105], v[120:121], v[90:91] op_sel_hi:[1,0]
	v_pk_mul_f32 v[106:107], v[122:123], v[90:91] op_sel_hi:[1,0]
	v_pk_mul_f32 v[108:109], v[124:125], v[90:91] op_sel_hi:[1,0]
	v_pk_mul_f32 v[110:111], v[126:127], v[90:91] op_sel_hi:[1,0]
	v_pk_mul_f32 v[90:91], v[128:129], v[90:91] op_sel_hi:[1,0]
	v_pk_fma_f32 v[92:93], v[10:11], v[92:93], v[6:7]
	v_pk_fma_f32 v[100:101], v[12:13], v[100:101], v[8:9]
	v_pk_fma_f32 v[102:103], v[18:19], v[102:103], v[2:3]
	v_pk_fma_f32 v[104:105], v[20:21], v[104:105], v[4:5]
	v_pk_fma_f32 v[108:109], v[24:25], v[108:109], v[32:33]
	v_pk_fma_f32 v[106:107], v[22:23], v[106:107], v[30:31]
	v_pk_fma_f32 v[112:113], v[16:17], v[90:91], v[28:29]
	v_pk_fma_f32 v[110:111], v[14:15], v[110:111], v[26:27]
	v_cvt_pk_bf16_f32 v90, v92, v93
	v_cvt_pk_bf16_f32 v91, v100, v101
	v_cvt_pk_bf16_f32 v92, v102, v103
	v_cvt_pk_bf16_f32 v93, v104, v105
	v_lshl_add_u64 v[68:69], v[64:65], 0, s[44:45]
	global_store_dwordx4 v[66:67], v[90:93], off sc1
	s_nop 1
	v_cvt_pk_bf16_f32 v34, v106, v107
	v_cvt_pk_bf16_f32 v35, v108, v109
	v_cvt_pk_bf16_f32 v36, v110, v111
	v_cvt_pk_bf16_f32 v37, v112, v113
	s_nop 0
	global_store_dwordx4 v[68:69], v[34:37], off sc1
	s_nop 1
	v_lshl_add_u64 v[64:65], v[64:65], 0, s[76:77]
	v_mov_b32_e32 v90, v73
	v_lshl_add_u64 v[66:67], v[64:65], 0, s[42:43]
	v_pk_mul_f32 v[92:93], v[130:131], v[90:91] op_sel_hi:[1,0]
	v_pk_mul_f32 v[100:101], v[132:133], v[90:91] op_sel_hi:[1,0]
	v_pk_mul_f32 v[102:103], v[134:135], v[90:91] op_sel_hi:[1,0]
	v_pk_mul_f32 v[104:105], v[136:137], v[90:91] op_sel_hi:[1,0]
	v_pk_mul_f32 v[106:107], v[138:139], v[90:91] op_sel_hi:[1,0]
	v_pk_mul_f32 v[108:109], v[140:141], v[90:91] op_sel_hi:[1,0]
	v_pk_mul_f32 v[110:111], v[142:143], v[90:91] op_sel_hi:[1,0]
	v_pk_mul_f32 v[90:91], v[144:145], v[90:91] op_sel_hi:[1,0]
	v_pk_fma_f32 v[92:93], v[10:11], v[92:93], v[6:7]
	v_pk_fma_f32 v[100:101], v[12:13], v[100:101], v[8:9]
	v_pk_fma_f32 v[102:103], v[18:19], v[102:103], v[2:3]
	v_pk_fma_f32 v[104:105], v[20:21], v[104:105], v[4:5]
	v_pk_fma_f32 v[108:109], v[24:25], v[108:109], v[32:33]
	v_pk_fma_f32 v[106:107], v[22:23], v[106:107], v[30:31]
	v_pk_fma_f32 v[112:113], v[16:17], v[90:91], v[28:29]
	v_pk_fma_f32 v[110:111], v[14:15], v[110:111], v[26:27]
	v_cvt_pk_bf16_f32 v90, v92, v93
	v_cvt_pk_bf16_f32 v91, v100, v101
	v_cvt_pk_bf16_f32 v92, v102, v103
	v_cvt_pk_bf16_f32 v93, v104, v105
	v_lshl_add_u64 v[68:69], v[64:65], 0, s[44:45]
	global_store_dwordx4 v[66:67], v[90:93], off sc1
	s_nop 1
	v_cvt_pk_bf16_f32 v34, v106, v107
	v_cvt_pk_bf16_f32 v35, v108, v109
	v_cvt_pk_bf16_f32 v36, v110, v111
	v_cvt_pk_bf16_f32 v37, v112, v113
	s_nop 0
	global_store_dwordx4 v[68:69], v[34:37], off sc1
	s_nop 1
	v_lshl_add_u64 v[64:65], v[64:65], 0, s[76:77]
	v_mov_b32_e32 v90, v74
	v_lshl_add_u64 v[66:67], v[64:65], 0, s[42:43]
	v_pk_mul_f32 v[92:93], v[146:147], v[90:91] op_sel_hi:[1,0]
	v_pk_mul_f32 v[100:101], v[148:149], v[90:91] op_sel_hi:[1,0]
	v_pk_mul_f32 v[102:103], v[150:151], v[90:91] op_sel_hi:[1,0]
	v_pk_mul_f32 v[104:105], v[152:153], v[90:91] op_sel_hi:[1,0]
	v_pk_mul_f32 v[106:107], v[154:155], v[90:91] op_sel_hi:[1,0]
	v_pk_mul_f32 v[108:109], v[156:157], v[90:91] op_sel_hi:[1,0]
	v_pk_mul_f32 v[110:111], v[158:159], v[90:91] op_sel_hi:[1,0]
	v_pk_mul_f32 v[90:91], v[160:161], v[90:91] op_sel_hi:[1,0]
	v_pk_fma_f32 v[92:93], v[10:11], v[92:93], v[6:7]
	v_pk_fma_f32 v[100:101], v[12:13], v[100:101], v[8:9]
	v_pk_fma_f32 v[102:103], v[18:19], v[102:103], v[2:3]
	v_pk_fma_f32 v[104:105], v[20:21], v[104:105], v[4:5]
	v_pk_fma_f32 v[108:109], v[24:25], v[108:109], v[32:33]
	v_pk_fma_f32 v[106:107], v[22:23], v[106:107], v[30:31]
	v_pk_fma_f32 v[112:113], v[16:17], v[90:91], v[28:29]
	v_pk_fma_f32 v[110:111], v[14:15], v[110:111], v[26:27]
	v_cvt_pk_bf16_f32 v90, v92, v93
	v_cvt_pk_bf16_f32 v91, v100, v101
	v_cvt_pk_bf16_f32 v92, v102, v103
	v_cvt_pk_bf16_f32 v93, v104, v105
	v_lshl_add_u64 v[68:69], v[64:65], 0, s[44:45]
	global_store_dwordx4 v[66:67], v[90:93], off sc1
	s_nop 1
	v_cvt_pk_bf16_f32 v34, v106, v107
	v_cvt_pk_bf16_f32 v35, v108, v109
	v_cvt_pk_bf16_f32 v36, v110, v111
	v_cvt_pk_bf16_f32 v37, v112, v113
	s_nop 0
	global_store_dwordx4 v[68:69], v[34:37], off sc1
	s_nop 1
	v_lshl_add_u64 v[64:65], v[64:65], 0, s[76:77]
	v_mov_b32_e32 v90, v75
	v_lshl_add_u64 v[66:67], v[64:65], 0, s[42:43]
	v_pk_mul_f32 v[92:93], v[162:163], v[90:91] op_sel_hi:[1,0]
	v_pk_mul_f32 v[100:101], v[164:165], v[90:91] op_sel_hi:[1,0]
	v_pk_mul_f32 v[102:103], v[166:167], v[90:91] op_sel_hi:[1,0]
	v_pk_mul_f32 v[104:105], v[168:169], v[90:91] op_sel_hi:[1,0]
	v_pk_mul_f32 v[106:107], v[170:171], v[90:91] op_sel_hi:[1,0]
	v_pk_mul_f32 v[108:109], v[172:173], v[90:91] op_sel_hi:[1,0]
	v_pk_mul_f32 v[110:111], v[174:175], v[90:91] op_sel_hi:[1,0]
	v_pk_mul_f32 v[90:91], v[176:177], v[90:91] op_sel_hi:[1,0]
	v_pk_fma_f32 v[92:93], v[10:11], v[92:93], v[6:7]
	v_pk_fma_f32 v[100:101], v[12:13], v[100:101], v[8:9]
	v_pk_fma_f32 v[102:103], v[18:19], v[102:103], v[2:3]
	v_pk_fma_f32 v[104:105], v[20:21], v[104:105], v[4:5]
	v_pk_fma_f32 v[108:109], v[24:25], v[108:109], v[32:33]
	v_pk_fma_f32 v[106:107], v[22:23], v[106:107], v[30:31]
	v_pk_fma_f32 v[112:113], v[16:17], v[90:91], v[28:29]
	v_pk_fma_f32 v[110:111], v[14:15], v[110:111], v[26:27]
	v_cvt_pk_bf16_f32 v90, v92, v93
	v_cvt_pk_bf16_f32 v91, v100, v101
	v_cvt_pk_bf16_f32 v92, v102, v103
	v_cvt_pk_bf16_f32 v93, v104, v105
	v_lshl_add_u64 v[68:69], v[64:65], 0, s[44:45]
	global_store_dwordx4 v[66:67], v[90:93], off sc1
	s_nop 1
	v_cvt_pk_bf16_f32 v34, v106, v107
	v_cvt_pk_bf16_f32 v35, v108, v109
	v_cvt_pk_bf16_f32 v36, v110, v111
	v_cvt_pk_bf16_f32 v37, v112, v113
	s_nop 0
	global_store_dwordx4 v[68:69], v[34:37], off sc1
	s_nop 1
	v_lshl_add_u64 v[64:65], v[64:65], 0, s[76:77]
	v_mov_b32_e32 v90, v76
	v_lshl_add_u64 v[66:67], v[64:65], 0, s[42:43]
	v_pk_mul_f32 v[92:93], v[178:179], v[90:91] op_sel_hi:[1,0]
	v_pk_mul_f32 v[100:101], v[180:181], v[90:91] op_sel_hi:[1,0]
	v_pk_mul_f32 v[102:103], v[182:183], v[90:91] op_sel_hi:[1,0]
	v_pk_mul_f32 v[104:105], v[184:185], v[90:91] op_sel_hi:[1,0]
	v_pk_mul_f32 v[106:107], v[186:187], v[90:91] op_sel_hi:[1,0]
	v_pk_mul_f32 v[108:109], v[188:189], v[90:91] op_sel_hi:[1,0]
	v_pk_mul_f32 v[110:111], v[190:191], v[90:91] op_sel_hi:[1,0]
	v_pk_mul_f32 v[90:91], v[192:193], v[90:91] op_sel_hi:[1,0]
	v_pk_fma_f32 v[92:93], v[10:11], v[92:93], v[6:7]
	v_pk_fma_f32 v[100:101], v[12:13], v[100:101], v[8:9]
	v_pk_fma_f32 v[102:103], v[18:19], v[102:103], v[2:3]
	v_pk_fma_f32 v[104:105], v[20:21], v[104:105], v[4:5]
	v_pk_fma_f32 v[108:109], v[24:25], v[108:109], v[32:33]
	v_pk_fma_f32 v[106:107], v[22:23], v[106:107], v[30:31]
	v_pk_fma_f32 v[112:113], v[16:17], v[90:91], v[28:29]
	v_pk_fma_f32 v[110:111], v[14:15], v[110:111], v[26:27]
	v_cvt_pk_bf16_f32 v90, v92, v93
	v_cvt_pk_bf16_f32 v91, v100, v101
	v_cvt_pk_bf16_f32 v92, v102, v103
	v_cvt_pk_bf16_f32 v93, v104, v105
	v_lshl_add_u64 v[68:69], v[64:65], 0, s[44:45]
	global_store_dwordx4 v[66:67], v[90:93], off sc1
	s_nop 1
	v_cvt_pk_bf16_f32 v34, v106, v107
	v_cvt_pk_bf16_f32 v35, v108, v109
	v_cvt_pk_bf16_f32 v36, v110, v111
	v_cvt_pk_bf16_f32 v37, v112, v113
	s_nop 0
	global_store_dwordx4 v[68:69], v[34:37], off sc1
	s_nop 1
	v_lshl_add_u64 v[64:65], v[64:65], 0, s[76:77]
	v_mov_b32_e32 v90, v77
	v_lshl_add_u64 v[66:67], v[64:65], 0, s[42:43]
	v_pk_mul_f32 v[92:93], v[194:195], v[90:91] op_sel_hi:[1,0]
	v_pk_mul_f32 v[100:101], v[196:197], v[90:91] op_sel_hi:[1,0]
	v_pk_mul_f32 v[102:103], v[198:199], v[90:91] op_sel_hi:[1,0]
	v_pk_mul_f32 v[104:105], v[200:201], v[90:91] op_sel_hi:[1,0]
	v_pk_mul_f32 v[106:107], v[202:203], v[90:91] op_sel_hi:[1,0]
	v_pk_mul_f32 v[108:109], v[204:205], v[90:91] op_sel_hi:[1,0]
	v_pk_mul_f32 v[110:111], v[206:207], v[90:91] op_sel_hi:[1,0]
	v_pk_mul_f32 v[90:91], v[208:209], v[90:91] op_sel_hi:[1,0]
	v_pk_fma_f32 v[92:93], v[10:11], v[92:93], v[6:7]
	v_pk_fma_f32 v[100:101], v[12:13], v[100:101], v[8:9]
	v_pk_fma_f32 v[102:103], v[18:19], v[102:103], v[2:3]
	v_pk_fma_f32 v[104:105], v[20:21], v[104:105], v[4:5]
	v_pk_fma_f32 v[108:109], v[24:25], v[108:109], v[32:33]
	v_pk_fma_f32 v[106:107], v[22:23], v[106:107], v[30:31]
	v_pk_fma_f32 v[112:113], v[16:17], v[90:91], v[28:29]
	v_pk_fma_f32 v[110:111], v[14:15], v[110:111], v[26:27]
	v_cvt_pk_bf16_f32 v90, v92, v93
	v_cvt_pk_bf16_f32 v91, v100, v101
	v_cvt_pk_bf16_f32 v92, v102, v103
	v_cvt_pk_bf16_f32 v93, v104, v105
	v_lshl_add_u64 v[68:69], v[64:65], 0, s[44:45]
	global_store_dwordx4 v[66:67], v[90:93], off sc1
	s_nop 1
	v_cvt_pk_bf16_f32 v34, v106, v107
	v_cvt_pk_bf16_f32 v35, v108, v109
	v_cvt_pk_bf16_f32 v36, v110, v111
	v_cvt_pk_bf16_f32 v37, v112, v113
	s_nop 0
	global_store_dwordx4 v[68:69], v[34:37], off sc1
	s_nop 1
	v_lshl_add_u64 v[64:65], v[64:65], 0, s[76:77]
	v_mov_b32_e32 v90, v78
	v_lshl_add_u64 v[66:67], v[64:65], 0, s[42:43]
	v_pk_mul_f32 v[92:93], v[210:211], v[90:91] op_sel_hi:[1,0]
	v_pk_mul_f32 v[100:101], v[212:213], v[90:91] op_sel_hi:[1,0]
	v_pk_mul_f32 v[102:103], v[214:215], v[90:91] op_sel_hi:[1,0]
	v_pk_mul_f32 v[104:105], v[216:217], v[90:91] op_sel_hi:[1,0]
	v_pk_mul_f32 v[106:107], v[218:219], v[90:91] op_sel_hi:[1,0]
	v_pk_mul_f32 v[108:109], v[220:221], v[90:91] op_sel_hi:[1,0]
	v_pk_mul_f32 v[110:111], v[222:223], v[90:91] op_sel_hi:[1,0]
	v_pk_mul_f32 v[90:91], v[224:225], v[90:91] op_sel_hi:[1,0]
	v_pk_fma_f32 v[92:93], v[10:11], v[92:93], v[6:7]
	v_pk_fma_f32 v[100:101], v[12:13], v[100:101], v[8:9]
	v_pk_fma_f32 v[102:103], v[18:19], v[102:103], v[2:3]
	v_pk_fma_f32 v[104:105], v[20:21], v[104:105], v[4:5]
	v_pk_fma_f32 v[108:109], v[24:25], v[108:109], v[32:33]
	v_pk_fma_f32 v[106:107], v[22:23], v[106:107], v[30:31]
	v_pk_fma_f32 v[112:113], v[16:17], v[90:91], v[28:29]
	v_pk_fma_f32 v[110:111], v[14:15], v[110:111], v[26:27]
	v_cvt_pk_bf16_f32 v90, v92, v93
	v_cvt_pk_bf16_f32 v91, v100, v101
	v_cvt_pk_bf16_f32 v92, v102, v103
	v_cvt_pk_bf16_f32 v93, v104, v105
	v_lshl_add_u64 v[68:69], v[64:65], 0, s[44:45]
	global_store_dwordx4 v[66:67], v[90:93], off sc1
	s_nop 1
	v_cvt_pk_bf16_f32 v34, v106, v107
	v_cvt_pk_bf16_f32 v35, v108, v109
	v_cvt_pk_bf16_f32 v36, v110, v111
	v_cvt_pk_bf16_f32 v37, v112, v113
	s_nop 0
	global_store_dwordx4 v[68:69], v[34:37], off sc1
	s_nop 1
	v_lshl_add_u64 v[64:65], v[64:65], 0, s[76:77]
	v_mov_b32_e32 v90, v79
	v_lshl_add_u64 v[66:67], v[64:65], 0, s[42:43]
	v_pk_mul_f32 v[92:93], v[226:227], v[90:91] op_sel_hi:[1,0]
	v_pk_mul_f32 v[100:101], v[228:229], v[90:91] op_sel_hi:[1,0]
	v_pk_mul_f32 v[102:103], v[230:231], v[90:91] op_sel_hi:[1,0]
	v_pk_mul_f32 v[104:105], v[232:233], v[90:91] op_sel_hi:[1,0]
	v_pk_mul_f32 v[106:107], v[234:235], v[90:91] op_sel_hi:[1,0]
	v_pk_mul_f32 v[108:109], v[236:237], v[90:91] op_sel_hi:[1,0]
	v_pk_mul_f32 v[110:111], v[238:239], v[90:91] op_sel_hi:[1,0]
	v_pk_mul_f32 v[90:91], v[240:241], v[90:91] op_sel_hi:[1,0]
	v_pk_fma_f32 v[92:93], v[10:11], v[92:93], v[6:7]
	v_pk_fma_f32 v[100:101], v[12:13], v[100:101], v[8:9]
	v_pk_fma_f32 v[102:103], v[18:19], v[102:103], v[2:3]
	v_pk_fma_f32 v[104:105], v[20:21], v[104:105], v[4:5]
	v_pk_fma_f32 v[108:109], v[24:25], v[108:109], v[32:33]
	v_pk_fma_f32 v[106:107], v[22:23], v[106:107], v[30:31]
	v_pk_fma_f32 v[112:113], v[16:17], v[90:91], v[28:29]
	v_pk_fma_f32 v[110:111], v[14:15], v[110:111], v[26:27]
	v_cvt_pk_bf16_f32 v90, v92, v93
	v_cvt_pk_bf16_f32 v91, v100, v101
	v_cvt_pk_bf16_f32 v92, v102, v103
	v_cvt_pk_bf16_f32 v93, v104, v105
	v_lshl_add_u64 v[68:69], v[64:65], 0, s[44:45]
	global_store_dwordx4 v[66:67], v[90:93], off sc1
	s_nop 1
	v_cvt_pk_bf16_f32 v34, v106, v107
	v_cvt_pk_bf16_f32 v35, v108, v109
	v_cvt_pk_bf16_f32 v36, v110, v111
	v_cvt_pk_bf16_f32 v37, v112, v113
	s_nop 0
	global_store_dwordx4 v[68:69], v[34:37], off sc1
	s_nop 1
	s_add_i32 s4, s4, s6
	v_lshl_add_u64 v[58:59], v[58:59], 0, s[22:23]
	s_cmpk_gt_i32 s4, 0x3fff
	v_lshl_add_u64 v[60:61], v[60:61], 0, s[36:37]
	s_cbranch_scc0 .LBB0_157
